# adds: phase W plain transpose jobs (w_branch_a/b, w_out, w_ple) issue their 8 tile loads together with one wait
# baseline (speedup 1.0000x reference)
; DI int opaque_bid() { int b = blockIdx.x; asm volatile("" : "+s"(b)); return b; }
; DI void transpose_job(const float* __restrict__ src, const float* __restrict__ gain, u16* __restrict__ dst, int K, int N, bool q8 = false) {
;     ...
;   for (int tile = opaque_bid(); tile < nk * nn; tile += gridDim.x) {
;     const int k0 = (tile / nn) << 6, n0 = (tile % nn) << 6;
; #pragma unroll
;     for (int i = 0; i < 8; ++i) {
;       int e = tid + i * NTHREADS, kk = e >> 6, c = e & 63;
;       float v = src[(size_t)(k0 + kk) * N + n0 + c];
;       if (gain) v *= gain[k0 + kk];
;       t[kk * 65 + c] = v;
;     }
;     __syncthreads();
; #pragma unroll
;     for (int i = 0; i < 8; ++i) {
;       int e = tid + i * NTHREADS, c = e >> 6, kk = e & 63;
;       if (q8) ((u8*)dst)[(size_t)(n0 + c) * K + k0 + kk] = (u8)(pk4_fp8(t[kk * 65 + c] * WQ_SCALE, 0.f, 0.f, 0.f) & 0xffu);
;       else dst[(size_t)(n0 + c) * K + k0 + kk] = (u16)(pk2(t[kk * 65 + c], 0.f) & 0xffffu);
;     }
;     __syncthreads();
.LBB0_605:
	s_ashr_i32 s4, s38, 31
	s_lshr_b32 s4, s4, 28
	s_add_i32 s4, s38, s4
	s_ashr_i32 s4, s4, 4
	s_lshl_b32 s36, s4, 6
	s_lshl_b32 s4, s4, 10
	s_sub_i32 s4, s51, s4
	v_add_u32_e32 v32, s36, v6
	s_ashr_i32 s5, s4, 31
	v_ashrrev_i32_e32 v33, 31, v32
	v_lshl_add_u64 v[30:31], s[4:5], 2, v[2:3]
	v_lshlrev_b64 v[32:33], 12, v[32:33]
	v_lshl_add_u64 v[32:33], v[30:31], 0, v[32:33]
	global_load_dword v56, v[32:33], off
	v_add_u32_e32 v32, s36, v7
	v_ashrrev_i32_e32 v33, 31, v32
	v_lshlrev_b64 v[32:33], 12, v[32:33]
	v_lshl_add_u64 v[32:33], v[30:31], 0, v[32:33]
	s_ashr_i32 s37, s36, 31
	s_add_i32 s38, s38, s39
	s_add_i32 s51, s51, s52
	s_cmpk_lt_i32 s38, 0x80
	global_load_dword v57, v[32:33], off
	v_add_u32_e32 v32, s36, v8
	v_ashrrev_i32_e32 v33, 31, v32
	v_lshlrev_b64 v[32:33], 12, v[32:33]
	v_lshl_add_u64 v[32:33], v[30:31], 0, v[32:33]
	global_load_dword v58, v[32:33], off
	v_add_u32_e32 v32, s36, v9
	v_ashrrev_i32_e32 v33, 31, v32
	v_lshlrev_b64 v[32:33], 12, v[32:33]
	v_lshl_add_u64 v[32:33], v[30:31], 0, v[32:33]
	global_load_dword v59, v[32:33], off
	v_add_u32_e32 v32, s36, v10
	v_ashrrev_i32_e32 v33, 31, v32
	v_lshlrev_b64 v[32:33], 12, v[32:33]
	v_lshl_add_u64 v[32:33], v[30:31], 0, v[32:33]
	global_load_dword v60, v[32:33], off
	v_add_u32_e32 v32, s36, v11
	v_ashrrev_i32_e32 v33, 31, v32
	v_lshlrev_b64 v[32:33], 12, v[32:33]
	v_lshl_add_u64 v[32:33], v[30:31], 0, v[32:33]
	global_load_dword v61, v[32:33], off
	v_add_u32_e32 v32, s36, v12
	v_ashrrev_i32_e32 v33, 31, v32
	v_lshlrev_b64 v[32:33], 12, v[32:33]
	v_lshl_add_u64 v[32:33], v[30:31], 0, v[32:33]
	global_load_dword v62, v[32:33], off
	v_add_u32_e32 v32, s36, v13
	v_ashrrev_i32_e32 v33, 31, v32
	v_lshlrev_b64 v[32:33], 12, v[32:33]
	v_lshl_add_u64 v[30:31], v[30:31], 0, v[32:33]
	v_add_u32_e32 v32, s4, v6
	v_ashrrev_i32_e32 v33, 31, v32
	v_lshlrev_b64 v[32:33], 10, v[32:33]
	global_load_dword v63, v[30:31], off
	v_lshl_add_u64 v[30:31], s[36:37], 1, v[4:5]
	v_lshl_add_u64 v[32:33], v[30:31], 0, v[32:33]
	s_waitcnt vmcnt(0)
	ds_write_b32 v22, v56
	ds_write_b32 v23, v57
	ds_write_b32 v24, v58
	ds_write_b32 v25, v59
	ds_write_b32 v26, v60
	ds_write_b32 v27, v61
	ds_write_b32 v28, v62
	ds_write_b32 v0, v63
	s_waitcnt lgkmcnt(0)
	s_barrier
	ds_read_b32 v29, v14
	s_waitcnt lgkmcnt(0)
	v_cvt_pk_bf16_f32 v29, v29, s0
	global_store_short v[32:33], v29, off
	ds_read_b32 v29, v15
	v_add_u32_e32 v32, s4, v7
	v_ashrrev_i32_e32 v33, 31, v32
	v_lshlrev_b64 v[32:33], 10, v[32:33]
	v_lshl_add_u64 v[32:33], v[30:31], 0, v[32:33]
	s_waitcnt lgkmcnt(0)
	v_cvt_pk_bf16_f32 v29, v29, s0
	global_store_short v[32:33], v29, off
	ds_read_b32 v29, v16
	v_add_u32_e32 v32, s4, v8
	v_ashrrev_i32_e32 v33, 31, v32
	v_lshlrev_b64 v[32:33], 10, v[32:33]
	v_lshl_add_u64 v[32:33], v[30:31], 0, v[32:33]
	s_waitcnt lgkmcnt(0)
	v_cvt_pk_bf16_f32 v29, v29, s0
	global_store_short v[32:33], v29, off
	ds_read_b32 v29, v17
	v_add_u32_e32 v32, s4, v9
	v_ashrrev_i32_e32 v33, 31, v32
	v_lshlrev_b64 v[32:33], 10, v[32:33]
	v_lshl_add_u64 v[32:33], v[30:31], 0, v[32:33]
	s_waitcnt lgkmcnt(0)
	v_cvt_pk_bf16_f32 v29, v29, s0
	global_store_short v[32:33], v29, off
	ds_read_b32 v29, v18
	v_add_u32_e32 v32, s4, v10
	v_ashrrev_i32_e32 v33, 31, v32
	v_lshlrev_b64 v[32:33], 10, v[32:33]
	v_lshl_add_u64 v[32:33], v[30:31], 0, v[32:33]
	s_waitcnt lgkmcnt(0)
	v_cvt_pk_bf16_f32 v29, v29, s0
	global_store_short v[32:33], v29, off
	ds_read_b32 v29, v19
	v_add_u32_e32 v32, s4, v11
	v_ashrrev_i32_e32 v33, 31, v32
	v_lshlrev_b64 v[32:33], 10, v[32:33]
	v_lshl_add_u64 v[32:33], v[30:31], 0, v[32:33]
	s_waitcnt lgkmcnt(0)
	v_cvt_pk_bf16_f32 v29, v29, s0
	global_store_short v[32:33], v29, off
	ds_read_b32 v29, v20
	v_add_u32_e32 v32, s4, v12
	v_ashrrev_i32_e32 v33, 31, v32
	v_lshlrev_b64 v[32:33], 10, v[32:33]
	v_lshl_add_u64 v[32:33], v[30:31], 0, v[32:33]
	s_waitcnt lgkmcnt(0)
	v_cvt_pk_bf16_f32 v29, v29, s0
	global_store_short v[32:33], v29, off
	ds_read_b32 v29, v21
	v_add_u32_e32 v32, s4, v13
	v_ashrrev_i32_e32 v33, 31, v32
	v_lshlrev_b64 v[32:33], 10, v[32:33]
	v_lshl_add_u64 v[30:31], v[30:31], 0, v[32:33]
	s_waitcnt lgkmcnt(0)
	v_cvt_pk_bf16_f32 v29, v29, s0
	global_store_short v[30:31], v29, off
	s_barrier
	s_cbranch_scc1 .LBB0_605

; DI int opaque_bid() { int b = blockIdx.x; asm volatile("" : "+s"(b)); return b; }
; DI void transpose_job(const float* __restrict__ src, const float* __restrict__ gain, u16* __restrict__ dst, int K, int N, bool q8 = false) {
;     ...
;   for (int tile = opaque_bid(); tile < nk * nn; tile += gridDim.x) {
;     const int k0 = (tile / nn) << 6, n0 = (tile % nn) << 6;
; #pragma unroll
;     for (int i = 0; i < 8; ++i) {
;       int e = tid + i * NTHREADS, kk = e >> 6, c = e & 63;
;       float v = src[(size_t)(k0 + kk) * N + n0 + c];
;       if (gain) v *= gain[k0 + kk];
;       t[kk * 65 + c] = v;
;     }
;     __syncthreads();
; #pragma unroll
;     for (int i = 0; i < 8; ++i) {
;       int e = tid + i * NTHREADS, c = e >> 6, kk = e & 63;
;       if (q8) ((u8*)dst)[(size_t)(n0 + c) * K + k0 + kk] = (u8)(pk4_fp8(t[kk * 65 + c] * WQ_SCALE, 0.f, 0.f, 0.f) & 0xffu);
;       else dst[(size_t)(n0 + c) * K + k0 + kk] = (u16)(pk2(t[kk * 65 + c], 0.f) & 0xffffu);
;     }
;     __syncthreads();
.LBB0_611:
	s_ashr_i32 s4, s51, 31
	s_lshr_b32 s4, s4, 28
	s_add_i32 s4, s51, s4
	s_ashr_i32 s4, s4, 4
	s_lshl_b32 s38, s4, 6
	s_lshl_b32 s4, s4, 10
	s_sub_i32 s4, s53, s4
	v_add_u32_e32 v32, s38, v6
	s_ashr_i32 s5, s4, 31
	v_ashrrev_i32_e32 v33, 31, v32
	v_lshl_add_u64 v[30:31], s[4:5], 2, v[2:3]
	v_lshlrev_b64 v[32:33], 12, v[32:33]
	v_lshl_add_u64 v[32:33], v[30:31], 0, v[32:33]
	global_load_dword v56, v[32:33], off
	v_add_u32_e32 v32, s38, v7
	v_ashrrev_i32_e32 v33, 31, v32
	v_lshlrev_b64 v[32:33], 12, v[32:33]
	v_lshl_add_u64 v[32:33], v[30:31], 0, v[32:33]
	s_ashr_i32 s39, s38, 31
	s_add_i32 s51, s51, s52
	s_add_i32 s53, s53, s54
	s_cmpk_lt_i32 s51, 0x100
	global_load_dword v57, v[32:33], off
	v_add_u32_e32 v32, s38, v8
	v_ashrrev_i32_e32 v33, 31, v32
	v_lshlrev_b64 v[32:33], 12, v[32:33]
	v_lshl_add_u64 v[32:33], v[30:31], 0, v[32:33]
	global_load_dword v58, v[32:33], off
	v_add_u32_e32 v32, s38, v9
	v_ashrrev_i32_e32 v33, 31, v32
	v_lshlrev_b64 v[32:33], 12, v[32:33]
	v_lshl_add_u64 v[32:33], v[30:31], 0, v[32:33]
	global_load_dword v59, v[32:33], off
	v_add_u32_e32 v32, s38, v10
	v_ashrrev_i32_e32 v33, 31, v32
	v_lshlrev_b64 v[32:33], 12, v[32:33]
	v_lshl_add_u64 v[32:33], v[30:31], 0, v[32:33]
	global_load_dword v60, v[32:33], off
	v_add_u32_e32 v32, s38, v11
	v_ashrrev_i32_e32 v33, 31, v32
	v_lshlrev_b64 v[32:33], 12, v[32:33]
	v_lshl_add_u64 v[32:33], v[30:31], 0, v[32:33]
	global_load_dword v61, v[32:33], off
	v_add_u32_e32 v32, s38, v12
	v_ashrrev_i32_e32 v33, 31, v32
	v_lshlrev_b64 v[32:33], 12, v[32:33]
	v_lshl_add_u64 v[32:33], v[30:31], 0, v[32:33]
	global_load_dword v62, v[32:33], off
	v_add_u32_e32 v32, s38, v13
	v_ashrrev_i32_e32 v33, 31, v32
	v_lshlrev_b64 v[32:33], 12, v[32:33]
	v_lshl_add_u64 v[30:31], v[30:31], 0, v[32:33]
	v_add_u32_e32 v32, s4, v6
	v_ashrrev_i32_e32 v33, 31, v32
	v_lshlrev_b64 v[32:33], 11, v[32:33]
	global_load_dword v63, v[30:31], off
	v_lshl_add_u64 v[30:31], s[38:39], 1, v[4:5]
	v_lshl_add_u64 v[32:33], v[30:31], 0, v[32:33]
	s_waitcnt vmcnt(0)
	ds_write_b32 v22, v56
	ds_write_b32 v23, v57
	ds_write_b32 v24, v58
	ds_write_b32 v25, v59
	ds_write_b32 v26, v60
	ds_write_b32 v27, v61
	ds_write_b32 v28, v62
	ds_write_b32 v0, v63
	s_waitcnt lgkmcnt(0)
	s_barrier
	ds_read_b32 v29, v14
	s_waitcnt lgkmcnt(0)
	v_cvt_pk_bf16_f32 v29, v29, s0
	global_store_short v[32:33], v29, off
	ds_read_b32 v29, v15
	v_add_u32_e32 v32, s4, v7
	v_ashrrev_i32_e32 v33, 31, v32
	v_lshlrev_b64 v[32:33], 11, v[32:33]
	v_lshl_add_u64 v[32:33], v[30:31], 0, v[32:33]
	s_waitcnt lgkmcnt(0)
	v_cvt_pk_bf16_f32 v29, v29, s0
	global_store_short v[32:33], v29, off
	ds_read_b32 v29, v16
	v_add_u32_e32 v32, s4, v8
	v_ashrrev_i32_e32 v33, 31, v32
	v_lshlrev_b64 v[32:33], 11, v[32:33]
	v_lshl_add_u64 v[32:33], v[30:31], 0, v[32:33]
	s_waitcnt lgkmcnt(0)
	v_cvt_pk_bf16_f32 v29, v29, s0
	global_store_short v[32:33], v29, off
	ds_read_b32 v29, v17
	v_add_u32_e32 v32, s4, v9
	v_ashrrev_i32_e32 v33, 31, v32
	v_lshlrev_b64 v[32:33], 11, v[32:33]
	v_lshl_add_u64 v[32:33], v[30:31], 0, v[32:33]
	s_waitcnt lgkmcnt(0)
	v_cvt_pk_bf16_f32 v29, v29, s0
	global_store_short v[32:33], v29, off
	ds_read_b32 v29, v18
	v_add_u32_e32 v32, s4, v10
	v_ashrrev_i32_e32 v33, 31, v32
	v_lshlrev_b64 v[32:33], 11, v[32:33]
	v_lshl_add_u64 v[32:33], v[30:31], 0, v[32:33]
	s_waitcnt lgkmcnt(0)
	v_cvt_pk_bf16_f32 v29, v29, s0
	global_store_short v[32:33], v29, off
	ds_read_b32 v29, v19
	v_add_u32_e32 v32, s4, v11
	v_ashrrev_i32_e32 v33, 31, v32
	v_lshlrev_b64 v[32:33], 11, v[32:33]
	v_lshl_add_u64 v[32:33], v[30:31], 0, v[32:33]
	s_waitcnt lgkmcnt(0)
	v_cvt_pk_bf16_f32 v29, v29, s0
	global_store_short v[32:33], v29, off
	ds_read_b32 v29, v20
	v_add_u32_e32 v32, s4, v12
	v_ashrrev_i32_e32 v33, 31, v32
	v_lshlrev_b64 v[32:33], 11, v[32:33]
	v_lshl_add_u64 v[32:33], v[30:31], 0, v[32:33]
	s_waitcnt lgkmcnt(0)
	v_cvt_pk_bf16_f32 v29, v29, s0
	global_store_short v[32:33], v29, off
	ds_read_b32 v29, v21
	v_add_u32_e32 v32, s4, v13
	v_ashrrev_i32_e32 v33, 31, v32
	v_lshlrev_b64 v[32:33], 11, v[32:33]
	v_lshl_add_u64 v[30:31], v[30:31], 0, v[32:33]
	s_waitcnt lgkmcnt(0)
	v_cvt_pk_bf16_f32 v29, v29, s0
	global_store_short v[30:31], v29, off
	s_barrier
	s_cbranch_scc1 .LBB0_611

; DI int opaque_bid() { int b = blockIdx.x; asm volatile("" : "+s"(b)); return b; }
; DI void transpose_job(const float* __restrict__ src, const float* __restrict__ gain, u16* __restrict__ dst, int K, int N, bool q8 = false) {
;     ...
;   for (int tile = opaque_bid(); tile < nk * nn; tile += gridDim.x) {
;     const int k0 = (tile / nn) << 6, n0 = (tile % nn) << 6;
; #pragma unroll
;     for (int i = 0; i < 8; ++i) {
;       int e = tid + i * NTHREADS, kk = e >> 6, c = e & 63;
;       float v = src[(size_t)(k0 + kk) * N + n0 + c];
;       if (gain) v *= gain[k0 + kk];
;       t[kk * 65 + c] = v;
;     }
;     __syncthreads();
; #pragma unroll
;     for (int i = 0; i < 8; ++i) {
;       int e = tid + i * NTHREADS, c = e >> 6, kk = e & 63;
;       if (q8) ((u8*)dst)[(size_t)(n0 + c) * K + k0 + kk] = (u8)(pk4_fp8(t[kk * 65 + c] * WQ_SCALE, 0.f, 0.f, 0.f) & 0xffu);
;       else dst[(size_t)(n0 + c) * K + k0 + kk] = (u16)(pk2(t[kk * 65 + c], 0.f) & 0xffffu);
;     }
;     __syncthreads();
.LBB0_633:
	s_ashr_i32 s4, s38, 31
	s_lshr_b32 s4, s4, 28
	s_add_i32 s4, s38, s4
	s_ashr_i32 s4, s4, 4
	s_lshl_b32 s30, s4, 6
	s_lshl_b32 s4, s4, 10
	s_sub_i32 s4, s35, s4
	v_add_u32_e32 v32, s30, v6
	s_ashr_i32 s5, s4, 31
	v_ashrrev_i32_e32 v33, 31, v32
	v_lshl_add_u64 v[30:31], s[4:5], 2, v[2:3]
	v_lshlrev_b64 v[32:33], 12, v[32:33]
	v_lshl_add_u64 v[32:33], v[30:31], 0, v[32:33]
	global_load_dword v56, v[32:33], off
	v_add_u32_e32 v32, s30, v7
	v_ashrrev_i32_e32 v33, 31, v32
	v_lshlrev_b64 v[32:33], 12, v[32:33]
	v_lshl_add_u64 v[32:33], v[30:31], 0, v[32:33]
	s_ashr_i32 s31, s30, 31
	s_add_i32 s38, s38, s34
	s_add_i32 s35, s35, s36
	s_cmp_lt_i32 s38, 64
	global_load_dword v57, v[32:33], off
	v_add_u32_e32 v32, s30, v8
	v_ashrrev_i32_e32 v33, 31, v32
	v_lshlrev_b64 v[32:33], 12, v[32:33]
	v_lshl_add_u64 v[32:33], v[30:31], 0, v[32:33]
	global_load_dword v58, v[32:33], off
	v_add_u32_e32 v32, s30, v9
	v_ashrrev_i32_e32 v33, 31, v32
	v_lshlrev_b64 v[32:33], 12, v[32:33]
	v_lshl_add_u64 v[32:33], v[30:31], 0, v[32:33]
	global_load_dword v59, v[32:33], off
	v_add_u32_e32 v32, s30, v10
	v_ashrrev_i32_e32 v33, 31, v32
	v_lshlrev_b64 v[32:33], 12, v[32:33]
	v_lshl_add_u64 v[32:33], v[30:31], 0, v[32:33]
	global_load_dword v60, v[32:33], off
	v_add_u32_e32 v32, s30, v11
	v_ashrrev_i32_e32 v33, 31, v32
	v_lshlrev_b64 v[32:33], 12, v[32:33]
	v_lshl_add_u64 v[32:33], v[30:31], 0, v[32:33]
	global_load_dword v61, v[32:33], off
	v_add_u32_e32 v32, s30, v12
	v_ashrrev_i32_e32 v33, 31, v32
	v_lshlrev_b64 v[32:33], 12, v[32:33]
	v_lshl_add_u64 v[32:33], v[30:31], 0, v[32:33]
	global_load_dword v62, v[32:33], off
	v_add_u32_e32 v32, s30, v13
	v_ashrrev_i32_e32 v33, 31, v32
	v_lshlrev_b64 v[32:33], 12, v[32:33]
	v_lshl_add_u64 v[30:31], v[30:31], 0, v[32:33]
	v_add_u32_e32 v32, s4, v6
	v_ashrrev_i32_e32 v33, 31, v32
	v_lshlrev_b64 v[32:33], 9, v[32:33]
	global_load_dword v63, v[30:31], off
	v_lshl_add_u64 v[30:31], s[30:31], 1, v[4:5]
	v_lshl_add_u64 v[32:33], v[30:31], 0, v[32:33]
	s_waitcnt vmcnt(0)
	ds_write_b32 v22, v56
	ds_write_b32 v23, v57
	ds_write_b32 v24, v58
	ds_write_b32 v25, v59
	ds_write_b32 v26, v60
	ds_write_b32 v27, v61
	ds_write_b32 v28, v62
	ds_write_b32 v0, v63
	s_waitcnt lgkmcnt(0)
	s_barrier
	ds_read_b32 v29, v14
	s_waitcnt lgkmcnt(0)
	v_cvt_pk_bf16_f32 v29, v29, s0
	global_store_short v[32:33], v29, off
	ds_read_b32 v29, v15
	v_add_u32_e32 v32, s4, v7
	v_ashrrev_i32_e32 v33, 31, v32
	v_lshlrev_b64 v[32:33], 9, v[32:33]
	v_lshl_add_u64 v[32:33], v[30:31], 0, v[32:33]
	s_waitcnt lgkmcnt(0)
	v_cvt_pk_bf16_f32 v29, v29, s0
	global_store_short v[32:33], v29, off
	ds_read_b32 v29, v16
	v_add_u32_e32 v32, s4, v8
	v_ashrrev_i32_e32 v33, 31, v32
	v_lshlrev_b64 v[32:33], 9, v[32:33]
	v_lshl_add_u64 v[32:33], v[30:31], 0, v[32:33]
	s_waitcnt lgkmcnt(0)
	v_cvt_pk_bf16_f32 v29, v29, s0
	global_store_short v[32:33], v29, off
	ds_read_b32 v29, v17
	v_add_u32_e32 v32, s4, v9
	v_ashrrev_i32_e32 v33, 31, v32
	v_lshlrev_b64 v[32:33], 9, v[32:33]
	v_lshl_add_u64 v[32:33], v[30:31], 0, v[32:33]
	s_waitcnt lgkmcnt(0)
	v_cvt_pk_bf16_f32 v29, v29, s0
	global_store_short v[32:33], v29, off
	ds_read_b32 v29, v18
	v_add_u32_e32 v32, s4, v10
	v_ashrrev_i32_e32 v33, 31, v32
	v_lshlrev_b64 v[32:33], 9, v[32:33]
	v_lshl_add_u64 v[32:33], v[30:31], 0, v[32:33]
	s_waitcnt lgkmcnt(0)
	v_cvt_pk_bf16_f32 v29, v29, s0
	global_store_short v[32:33], v29, off
	ds_read_b32 v29, v19
	v_add_u32_e32 v32, s4, v11
	v_ashrrev_i32_e32 v33, 31, v32
	v_lshlrev_b64 v[32:33], 9, v[32:33]
	v_lshl_add_u64 v[32:33], v[30:31], 0, v[32:33]
	s_waitcnt lgkmcnt(0)
	v_cvt_pk_bf16_f32 v29, v29, s0
	global_store_short v[32:33], v29, off
	ds_read_b32 v29, v20
	v_add_u32_e32 v32, s4, v12
	v_ashrrev_i32_e32 v33, 31, v32
	v_lshlrev_b64 v[32:33], 9, v[32:33]
	v_lshl_add_u64 v[32:33], v[30:31], 0, v[32:33]
	s_waitcnt lgkmcnt(0)
	v_cvt_pk_bf16_f32 v29, v29, s0
	global_store_short v[32:33], v29, off
	ds_read_b32 v29, v21
	v_add_u32_e32 v32, s4, v13
	v_ashrrev_i32_e32 v33, 31, v32
	v_lshlrev_b64 v[32:33], 9, v[32:33]
	v_lshl_add_u64 v[30:31], v[30:31], 0, v[32:33]
	s_waitcnt lgkmcnt(0)
	v_cvt_pk_bf16_f32 v29, v29, s0
	global_store_short v[30:31], v29, off
	s_barrier
	s_cbranch_scc1 .LBB0_633
	s_branch .LBB0_583

; #define LOAD_PARAMS() KParams kq_ = (KParams)__builtin_amdgcn_kernarg_segment_ptr(); asm volatile("" : "+s"(kq_)); const Params p = *kq_
; template <int CT>
; __global__ void __launch_bounds__(NTHREADS) mega_kernel(Params p) {
;     ...
; #pragma unroll 1
;   for (int ph = 0; ph < nph; ++ph) {
;     run_phase<CT>(ph);
;     if (ph + 1 < nph) {
;       LOAD_PARAMS();
;       xcd_barrier((unsigned*)(p.ws + WS<CT>::bar), x, nloc, nx, k);
;       ++k;
;     }
;   }
; }
.LBB0_726:
	s_endpgm
	s_nop 0
	s_nop 0
	s_nop 0
	s_nop 0
	s_nop 0
	s_nop 0
	s_nop 0
	s_nop 0
	s_nop 0
	s_nop 0
	s_nop 0
	s_nop 0
	s_nop 0
	s_nop 0
	s_nop 0
	s_nop 0
	s_nop 0
	s_nop 0
	s_nop 0
	s_nop 0
	s_nop 0
	s_nop 0
	s_nop 0
	s_nop 0
	s_nop 0
	s_nop 0
	s_nop 0
	s_nop 0
	s_nop 0
	s_nop 0
	s_nop 0
	s_nop 0
	s_nop 0
	s_nop 0
	s_nop 0
	s_nop 0
	s_nop 0
	s_nop 0
	s_nop 0
	s_nop 0
	s_nop 0
	s_nop 0
	s_nop 0
	s_nop 0
	s_nop 0
	s_nop 0
	s_nop 0
	s_nop 0
	s_nop 0
	s_nop 0
	s_nop 0
	s_nop 0
	s_nop 0
	s_nop 0
	s_nop 0
	s_nop 0
	s_nop 0
	s_nop 0
	s_nop 0
	s_endpgm
